# p0_mod: the five silu(c) strip loads of a chunk issued together with one wait (was load, wait, silu, store five times per chunk)
# speedup vs baseline: 1.0238x; 1.0120x over previous
.LBB0_136:
	s_lshl_b32 s0, s7, 7
	s_add_i32 s6, s7, 1
	s_bitcmp1_b32 s6, 0
	s_cselect_b32 s1, 0x500, 0
	s_addk_i32 s0, 0x80
	s_cmp_lg_u32 s7, 31
	s_cselect_b32 s17, s0, 0xf80
	v_add_u32_e32 v2, s17, v178
	v_add_u32_e32 v4, s1, v177
	s_mov_b64 s[4:5], 0
	v_mov_b32_e32 v5, v1
	v_cmp_gt_u32_e64 s[0:1], 32, v1
	v_mov_b32_e32 v38, s9
	v_mov_b32_e32 v39, s8
	v_mov_b32_e32 v40, s71
	v_mov_b32_e32 v41, s69
	v_cndmask_b32_e64 v44, v38, v39, s[0:1]
	v_mov_b32_e32 v42, s70
	v_mov_b32_e32 v43, s68
	v_cndmask_b32_e64 v39, v40, v41, s[0:1]
	v_add_u32_e32 v40, v44, v2
	v_cndmask_b32_e64 v38, v42, v43, s[0:1]
	v_ashrrev_i32_e32 v41, 31, v40
	v_lshl_add_u64 v[38:39], v[40:41], 2, v[38:39]
	global_load_dword v45, v[38:39], off
	v_add_u32_e32 v40, s9, v2
	v_add_u32_e32 v40, 0x4000, v40
	v_ashrrev_i32_e32 v41, 31, v40
	v_lshl_add_u64 v[38:39], v[40:41], 2, s[70:71]
	global_load_dword v46, v[38:39], off
	v_add_u32_e32 v40, 0x4000, v40
	v_ashrrev_i32_e32 v41, 31, v40
	v_lshl_add_u64 v[38:39], v[40:41], 2, s[70:71]
	global_load_dword v47, v[38:39], off
	v_add_u32_e32 v40, 0x4000, v40
	v_ashrrev_i32_e32 v41, 31, v40
	v_lshl_add_u64 v[38:39], v[40:41], 2, s[70:71]
	global_load_dword v48, v[38:39], off
	v_add_u32_e32 v40, 0x4000, v40
	v_ashrrev_i32_e32 v41, 31, v40
	v_lshl_add_u64 v[38:39], v[40:41], 2, s[70:71]
	s_and_saveexec_b64 s[4:5], s[0:1]
	global_load_dword v49, v[38:39], off
	s_mov_b64 exec, s[4:5]
	s_waitcnt vmcnt(0)
	v_mul_f32_e32 v50, 0xbfb8aa3b, v45
	v_mul_f32_e32 v51, 0xbfb8aa3b, v46
	v_mul_f32_e32 v52, 0xbfb8aa3b, v47
	v_mul_f32_e32 v53, 0xbfb8aa3b, v48
	v_mul_f32_e32 v54, 0xbfb8aa3b, v49
	v_exp_f32_e32 v50, v50
	v_exp_f32_e32 v51, v51
	v_exp_f32_e32 v52, v52
	v_exp_f32_e32 v53, v53
	v_exp_f32_e32 v54, v54
	v_add_f32_e32 v50, 1.0, v50
	v_add_f32_e32 v51, 1.0, v51
	v_add_f32_e32 v52, 1.0, v52
	v_add_f32_e32 v53, 1.0, v53
	v_add_f32_e32 v54, 1.0, v54
	v_rcp_f32_e32 v50, v50
	v_rcp_f32_e32 v51, v51
	v_rcp_f32_e32 v52, v52
	v_rcp_f32_e32 v53, v53
	v_rcp_f32_e32 v54, v54
	v_mul_f32_e32 v45, v45, v50
	v_mul_f32_e32 v46, v46, v51
	v_mul_f32_e32 v47, v47, v52
	v_mul_f32_e32 v48, v48, v53
	v_mul_f32_e32 v49, v49, v54
	ds_write_b32 v4, v45
	ds_write_b32 v4, v46 offset:16
	ds_write_b32 v4, v47 offset:32
	ds_write_b32 v4, v48 offset:48
	s_and_saveexec_b64 s[4:5], s[0:1]
	ds_write_b32 v4, v49 offset:64
	s_mov_b64 exec, s[4:5]
	s_or_b64 exec, exec, s[4:5]
	s_waitcnt lgkmcnt(0)
	s_and_saveexec_b64 s[0:1], vcc
	s_cbranch_execz .LBB0_140
	v_add_u32_e32 v2, s17, v143
	v_add_u32_e32 v38, 2, v2
	v_mad_i64_i32 v[4:5], s[4:5], v2, s12, v[168:169]
	v_mad_i64_i32 v[42:43], s[4:5], v38, s12, v[168:169]
	global_load_dwordx4 v[38:41], v[4:5], off
	s_nop 0
	global_load_dwordx4 v[42:45], v[42:43], off
	v_or_b32_e32 v4, 4, v2
	v_add_u32_e32 v46, 6, v2
	v_mad_i64_i32 v[4:5], s[4:5], v4, s12, v[168:169]
	v_mad_i64_i32 v[50:51], s[4:5], v46, s12, v[168:169]
	global_load_dwordx4 v[46:49], v[4:5], off
	s_nop 0
	global_load_dwordx4 v[50:53], v[50:51], off
	v_or_b32_e32 v4, 8, v2
	v_add_u32_e32 v54, 10, v2
	s_bitcmp1_b32 s7, 0
	v_mad_i64_i32 v[4:5], s[4:5], v4, s12, v[168:169]
	v_mad_i64_i32 v[58:59], s[4:5], v54, s12, v[168:169]
	s_cselect_b32 s7, 0x500, 0
	global_load_dwordx4 v[54:57], v[4:5], off
	s_nop 0
	global_load_dwordx4 v[58:61], v[58:59], off
	v_or_b32_e32 v4, 12, v2
	v_add_u32_e32 v2, 14, v2
	v_mad_i64_i32 v[4:5], s[4:5], v4, s12, v[168:169]
	v_add_u32_e32 v208, s7, v147
	v_mad_i64_i32 v[66:67], s[4:5], v2, s12, v[168:169]
	ds_read_b128 v[180:183], v208
	ds_read_b128 v[184:187], v208 offset:16
	ds_read_b128 v[188:191], v208 offset:32
	ds_read_b128 v[192:195], v208 offset:48
	global_load_dwordx4 v[62:65], v[4:5], off
	s_nop 0
	global_load_dwordx4 v[66:69], v[66:67], off
	s_waitcnt lgkmcnt(2)
	v_pk_fma_f32 v[200:201], v[34:35], v[184:185], v[74:75] op_sel_hi:[1,0,1]
	s_waitcnt lgkmcnt(1)
	v_pk_fma_f32 v[204:205], v[34:35], v[188:189], v[70:71] op_sel_hi:[1,0,1]
	v_pk_fma_f32 v[206:207], v[36:37], v[188:189], v[72:73] op_sel_hi:[1,0,1]
	ds_read2_b64 v[70:73], v208 offset0:8 offset1:28
	v_mov_b32_e32 v2, v183
	v_pk_fma_f32 v[202:203], v[36:37], v[184:185], v[76:77] op_sel_hi:[1,0,1]
	v_pk_fma_f32 v[4:5], v[34:35], v[2:3], v[114:115] op_sel_hi:[1,0,1]
	v_pk_fma_f32 v[114:115], v[36:37], v[2:3], v[116:117] op_sel_hi:[1,0,1]
	v_mov_b32_e32 v2, v187
	ds_read_b128 v[74:77], v208 offset:160
	v_pk_fma_f32 v[110:111], v[34:35], v[2:3], v[110:111] op_sel_hi:[1,0,1]
	v_pk_fma_f32 v[112:113], v[36:37], v[2:3], v[112:113] op_sel_hi:[1,0,1]
	v_mov_b32_e32 v2, v191
	v_pk_fma_f32 v[116:117], v[34:35], v[2:3], v[126:127] op_sel_hi:[1,0,1]
	v_pk_fma_f32 v[126:127], v[36:37], v[2:3], v[128:129] op_sel_hi:[1,0,1]
	s_waitcnt lgkmcnt(2)
	v_mov_b32_e32 v2, v195
	v_pk_fma_f32 v[196:197], v[34:35], v[180:181], v[82:83] op_sel_hi:[1,0,1]
	v_pk_fma_f32 v[198:199], v[36:37], v[180:181], v[84:85] op_sel_hi:[1,0,1]
	v_pk_fma_f32 v[90:91], v[34:35], v[192:193], v[90:91] op_sel_hi:[1,0,1]
	v_pk_fma_f32 v[92:93], v[36:37], v[192:193], v[92:93] op_sel_hi:[1,0,1]
	v_pk_fma_f32 v[94:95], v[34:35], v[180:181], v[94:95] op_sel:[0,1,0]
	v_pk_fma_f32 v[96:97], v[36:37], v[180:181], v[96:97] op_sel:[0,1,0]
	v_pk_fma_f32 v[86:87], v[34:35], v[184:185], v[86:87] op_sel:[0,1,0]
	v_pk_fma_f32 v[88:89], v[36:37], v[184:185], v[88:89] op_sel:[0,1,0]
	v_pk_fma_f32 v[180:181], v[34:35], v[188:189], v[78:79] op_sel:[0,1,0]
	v_pk_fma_f32 v[184:185], v[36:37], v[188:189], v[80:81] op_sel:[0,1,0]
	v_pk_fma_f32 v[106:107], v[34:35], v[192:193], v[106:107] op_sel:[0,1,0]
	v_pk_fma_f32 v[108:109], v[36:37], v[192:193], v[108:109] op_sel:[0,1,0]
	v_pk_fma_f32 v[102:103], v[34:35], v[182:183], v[102:103] op_sel_hi:[1,0,1]
	v_pk_fma_f32 v[104:105], v[36:37], v[182:183], v[104:105] op_sel_hi:[1,0,1]
	v_pk_fma_f32 v[98:99], v[34:35], v[186:187], v[98:99] op_sel_hi:[1,0,1]
	v_pk_fma_f32 v[100:101], v[36:37], v[186:187], v[100:101] op_sel_hi:[1,0,1]
	v_pk_fma_f32 v[118:119], v[34:35], v[190:191], v[118:119] op_sel_hi:[1,0,1]
	v_pk_fma_f32 v[120:121], v[36:37], v[190:191], v[120:121] op_sel_hi:[1,0,1]
	v_pk_fma_f32 v[122:123], v[34:35], v[194:195], v[122:123] op_sel_hi:[1,0,1]
	v_pk_fma_f32 v[124:125], v[36:37], v[194:195], v[124:125] op_sel_hi:[1,0,1]
	v_pk_fma_f32 v[128:129], v[34:35], v[2:3], v[130:131] op_sel_hi:[1,0,1]
	v_pk_fma_f32 v[130:131], v[36:37], v[2:3], v[132:133] op_sel_hi:[1,0,1]
	s_waitcnt lgkmcnt(1)
	v_pk_fma_f32 v[132:133], v[34:35], v[70:71], v[134:135] op_sel_hi:[1,0,1]
	v_pk_fma_f32 v[134:135], v[36:37], v[70:71], v[136:137] op_sel_hi:[1,0,1]
	v_pk_fma_f32 v[136:137], v[34:35], v[70:71], v[138:139] op_sel:[0,1,0]
	v_pk_fma_f32 v[70:71], v[36:37], v[70:71], v[140:141] op_sel:[0,1,0]
	ds_read_b128 v[34:37], v208 offset:176
	ds_read_b128 v[78:81], v208 offset:192
	ds_read_b128 v[82:85], v208 offset:208
	s_waitcnt lgkmcnt(3)
	v_mov_b32_e32 v2, v77
	v_pk_fma_f32 v[114:115], v[32:33], v[2:3], v[114:115] op_sel_hi:[1,0,1]
	v_pk_fma_f32 v[4:5], v[30:31], v[2:3], v[4:5] op_sel_hi:[1,0,1]
	s_waitcnt lgkmcnt(2)
	v_mov_b32_e32 v2, v37
	v_pk_fma_f32 v[112:113], v[32:33], v[2:3], v[112:113] op_sel_hi:[1,0,1]
	v_pk_fma_f32 v[110:111], v[30:31], v[2:3], v[110:111] op_sel_hi:[1,0,1]
	s_waitcnt lgkmcnt(1)
	v_mov_b32_e32 v2, v81
	s_waitcnt lgkmcnt(0)
	v_pk_fma_f32 v[92:93], v[32:33], v[82:83], v[92:93] op_sel_hi:[1,0,1]
	v_pk_fma_f32 v[90:91], v[30:31], v[82:83], v[90:91] op_sel_hi:[1,0,1]
	v_pk_fma_f32 v[108:109], v[32:33], v[82:83], v[108:109] op_sel:[0,1,0]
	v_pk_fma_f32 v[82:83], v[30:31], v[82:83], v[106:107] op_sel:[0,1,0]
	v_pk_fma_f32 v[106:107], v[32:33], v[80:81], v[120:121] op_sel_hi:[1,0,1]
	v_pk_fma_f32 v[120:121], v[32:33], v[84:85], v[124:125] op_sel_hi:[1,0,1]
	v_pk_fma_f32 v[124:125], v[32:33], v[2:3], v[126:127] op_sel_hi:[1,0,1]
	v_pk_fma_f32 v[116:117], v[30:31], v[2:3], v[116:117] op_sel_hi:[1,0,1]
	v_mov_b32_e32 v2, v85
	v_pk_fma_f32 v[138:139], v[32:33], v[74:75], v[198:199] op_sel_hi:[1,0,1]
	v_pk_fma_f32 v[140:141], v[30:31], v[74:75], v[196:197] op_sel_hi:[1,0,1]
	v_pk_fma_f32 v[182:183], v[32:33], v[34:35], v[202:203] op_sel_hi:[1,0,1]
	v_pk_fma_f32 v[186:187], v[30:31], v[34:35], v[200:201] op_sel_hi:[1,0,1]
	v_pk_fma_f32 v[188:189], v[32:33], v[78:79], v[206:207] op_sel_hi:[1,0,1]
	v_pk_fma_f32 v[190:191], v[30:31], v[78:79], v[204:205] op_sel_hi:[1,0,1]
	v_pk_fma_f32 v[96:97], v[32:33], v[74:75], v[96:97] op_sel:[0,1,0]
	v_pk_fma_f32 v[94:95], v[30:31], v[74:75], v[94:95] op_sel:[0,1,0]
	v_pk_fma_f32 v[88:89], v[32:33], v[34:35], v[88:89] op_sel:[0,1,0]
	v_pk_fma_f32 v[86:87], v[30:31], v[34:35], v[86:87] op_sel:[0,1,0]
	v_pk_fma_f32 v[184:185], v[32:33], v[78:79], v[184:185] op_sel:[0,1,0]
	v_pk_fma_f32 v[180:181], v[30:31], v[78:79], v[180:181] op_sel:[0,1,0]
	v_pk_fma_f32 v[104:105], v[32:33], v[76:77], v[104:105] op_sel_hi:[1,0,1]
	v_pk_fma_f32 v[102:103], v[30:31], v[76:77], v[102:103] op_sel_hi:[1,0,1]
	v_pk_fma_f32 v[100:101], v[32:33], v[36:37], v[100:101] op_sel_hi:[1,0,1]
	v_pk_fma_f32 v[98:99], v[30:31], v[36:37], v[98:99] op_sel_hi:[1,0,1]
	v_pk_fma_f32 v[118:119], v[30:31], v[80:81], v[118:119] op_sel_hi:[1,0,1]
	v_pk_fma_f32 v[122:123], v[30:31], v[84:85], v[122:123] op_sel_hi:[1,0,1]
	v_pk_fma_f32 v[84:85], v[32:33], v[2:3], v[130:131] op_sel_hi:[1,0,1]
	v_pk_fma_f32 v[126:127], v[30:31], v[2:3], v[128:129] op_sel_hi:[1,0,1]
	v_pk_fma_f32 v[128:129], v[32:33], v[72:73], v[134:135] op_sel_hi:[1,0,1]
	v_pk_fma_f32 v[130:131], v[30:31], v[72:73], v[132:133] op_sel_hi:[1,0,1]
	v_pk_fma_f32 v[132:133], v[32:33], v[72:73], v[70:71] op_sel:[0,1,0]
	v_pk_fma_f32 v[134:135], v[30:31], v[72:73], v[136:137] op_sel:[0,1,0]
	ds_read_b128 v[30:33], v208 offset:320
	ds_read_b128 v[34:37], v208 offset:336
	ds_read_b128 v[70:73], v208 offset:352
	ds_read_b128 v[74:77], v208 offset:368
	ds_read2_b64 v[78:81], v208 offset0:48 offset1:68
	s_waitcnt lgkmcnt(4)
	v_mov_b32_e32 v2, v33
	v_pk_fma_f32 v[136:137], v[26:27], v[30:31], v[140:141] op_sel_hi:[1,0,1]
	v_pk_fma_f32 v[138:139], v[28:29], v[30:31], v[138:139] op_sel_hi:[1,0,1]
	v_pk_fma_f32 v[94:95], v[26:27], v[30:31], v[94:95] op_sel:[0,1,0]
	v_pk_fma_f32 v[96:97], v[28:29], v[30:31], v[96:97] op_sel:[0,1,0]
	v_pk_fma_f32 v[102:103], v[26:27], v[32:33], v[102:103] op_sel_hi:[1,0,1]
	v_pk_fma_f32 v[104:105], v[28:29], v[32:33], v[104:105] op_sel_hi:[1,0,1]
	v_pk_fma_f32 v[4:5], v[26:27], v[2:3], v[4:5] op_sel_hi:[1,0,1]
	v_pk_fma_f32 v[114:115], v[28:29], v[2:3], v[114:115] op_sel_hi:[1,0,1]
	s_waitcnt lgkmcnt(3)
	v_mov_b32_e32 v2, v37
	ds_read_b128 v[30:33], v208 offset:480
	v_pk_fma_f32 v[110:111], v[26:27], v[2:3], v[110:111] op_sel_hi:[1,0,1]
	v_pk_fma_f32 v[112:113], v[28:29], v[2:3], v[112:113] op_sel_hi:[1,0,1]
	s_waitcnt lgkmcnt(3)
	v_mov_b32_e32 v2, v73
	s_waitcnt lgkmcnt(2)
	v_pk_fma_f32 v[90:91], v[26:27], v[74:75], v[90:91] op_sel_hi:[1,0,1]
	v_pk_fma_f32 v[92:93], v[28:29], v[74:75], v[92:93] op_sel_hi:[1,0,1]
	v_pk_fma_f32 v[82:83], v[26:27], v[74:75], v[82:83] op_sel:[0,1,0]
	v_pk_fma_f32 v[74:75], v[28:29], v[74:75], v[108:109] op_sel:[0,1,0]
	v_pk_fma_f32 v[108:109], v[26:27], v[72:73], v[118:119] op_sel_hi:[1,0,1]
	v_pk_fma_f32 v[118:119], v[26:27], v[76:77], v[122:123] op_sel_hi:[1,0,1]
	v_pk_fma_f32 v[116:117], v[26:27], v[2:3], v[116:117] op_sel_hi:[1,0,1]
	v_pk_fma_f32 v[122:123], v[28:29], v[2:3], v[124:125] op_sel_hi:[1,0,1]
	v_mov_b32_e32 v2, v77
	v_pk_fma_f32 v[140:141], v[26:27], v[34:35], v[186:187] op_sel_hi:[1,0,1]
	v_pk_fma_f32 v[182:183], v[28:29], v[34:35], v[182:183] op_sel_hi:[1,0,1]
	v_pk_fma_f32 v[186:187], v[26:27], v[70:71], v[190:191] op_sel_hi:[1,0,1]
	v_pk_fma_f32 v[188:189], v[28:29], v[70:71], v[188:189] op_sel_hi:[1,0,1]
	v_pk_fma_f32 v[86:87], v[26:27], v[34:35], v[86:87] op_sel:[0,1,0]
	v_pk_fma_f32 v[88:89], v[28:29], v[34:35], v[88:89] op_sel:[0,1,0]
	v_pk_fma_f32 v[180:181], v[26:27], v[70:71], v[180:181] op_sel:[0,1,0]
	v_pk_fma_f32 v[184:185], v[28:29], v[70:71], v[184:185] op_sel:[0,1,0]
	v_pk_fma_f32 v[98:99], v[26:27], v[36:37], v[98:99] op_sel_hi:[1,0,1]
	v_pk_fma_f32 v[100:101], v[28:29], v[36:37], v[100:101] op_sel_hi:[1,0,1]
	v_pk_fma_f32 v[106:107], v[28:29], v[72:73], v[106:107] op_sel_hi:[1,0,1]
	v_pk_fma_f32 v[120:121], v[28:29], v[76:77], v[120:121] op_sel_hi:[1,0,1]
	v_pk_fma_f32 v[76:77], v[26:27], v[2:3], v[126:127] op_sel_hi:[1,0,1]
	v_pk_fma_f32 v[84:85], v[28:29], v[2:3], v[84:85] op_sel_hi:[1,0,1]
	s_waitcnt lgkmcnt(1)
	v_pk_fma_f32 v[124:125], v[26:27], v[78:79], v[130:131] op_sel_hi:[1,0,1]
	v_pk_fma_f32 v[126:127], v[28:29], v[78:79], v[128:129] op_sel_hi:[1,0,1]
	v_pk_fma_f32 v[128:129], v[26:27], v[78:79], v[134:135] op_sel:[0,1,0]
	v_pk_fma_f32 v[78:79], v[28:29], v[78:79], v[132:133] op_sel:[0,1,0]
	ds_read_b128 v[26:29], v208 offset:496
	ds_read_b128 v[34:37], v208 offset:512
	ds_read_b128 v[70:73], v208 offset:528
	s_waitcnt lgkmcnt(3)
	v_mov_b32_e32 v2, v33
	v_pk_fma_f32 v[114:115], v[24:25], v[2:3], v[114:115] op_sel_hi:[1,0,1]
	v_pk_fma_f32 v[4:5], v[22:23], v[2:3], v[4:5] op_sel_hi:[1,0,1]
	s_waitcnt lgkmcnt(2)
	v_mov_b32_e32 v2, v29
	v_pk_fma_f32 v[112:113], v[24:25], v[2:3], v[112:113] op_sel_hi:[1,0,1]
	v_pk_fma_f32 v[110:111], v[22:23], v[2:3], v[110:111] op_sel_hi:[1,0,1]
	s_waitcnt lgkmcnt(1)
	v_mov_b32_e32 v2, v37
	v_pk_fma_f32 v[122:123], v[24:25], v[2:3], v[122:123] op_sel_hi:[1,0,1]
	v_pk_fma_f32 v[116:117], v[22:23], v[2:3], v[116:117] op_sel_hi:[1,0,1]
	s_waitcnt lgkmcnt(0)
	v_mov_b32_e32 v2, v73
	v_pk_fma_f32 v[130:131], v[24:25], v[30:31], v[138:139] op_sel_hi:[1,0,1]
	v_pk_fma_f32 v[132:133], v[22:23], v[30:31], v[136:137] op_sel_hi:[1,0,1]
	v_pk_fma_f32 v[134:135], v[24:25], v[26:27], v[182:183] op_sel_hi:[1,0,1]
	v_pk_fma_f32 v[136:137], v[22:23], v[26:27], v[140:141] op_sel_hi:[1,0,1]
	v_pk_fma_f32 v[138:139], v[24:25], v[34:35], v[188:189] op_sel_hi:[1,0,1]
	v_pk_fma_f32 v[140:141], v[22:23], v[34:35], v[186:187] op_sel_hi:[1,0,1]
	v_pk_fma_f32 v[92:93], v[24:25], v[70:71], v[92:93] op_sel_hi:[1,0,1]
	v_pk_fma_f32 v[90:91], v[22:23], v[70:71], v[90:91] op_sel_hi:[1,0,1]
	v_pk_fma_f32 v[96:97], v[24:25], v[30:31], v[96:97] op_sel:[0,1,0]
	v_pk_fma_f32 v[94:95], v[22:23], v[30:31], v[94:95] op_sel:[0,1,0]
	v_pk_fma_f32 v[88:89], v[24:25], v[26:27], v[88:89] op_sel:[0,1,0]
	v_pk_fma_f32 v[86:87], v[22:23], v[26:27], v[86:87] op_sel:[0,1,0]
	v_pk_fma_f32 v[182:183], v[24:25], v[34:35], v[184:185] op_sel:[0,1,0]
	v_pk_fma_f32 v[180:181], v[22:23], v[34:35], v[180:181] op_sel:[0,1,0]
	v_pk_fma_f32 v[74:75], v[24:25], v[70:71], v[74:75] op_sel:[0,1,0]
	v_pk_fma_f32 v[82:83], v[22:23], v[70:71], v[82:83] op_sel:[0,1,0]
	v_pk_fma_f32 v[104:105], v[24:25], v[32:33], v[104:105] op_sel_hi:[1,0,1]
	v_pk_fma_f32 v[102:103], v[22:23], v[32:33], v[102:103] op_sel_hi:[1,0,1]
	v_pk_fma_f32 v[100:101], v[24:25], v[28:29], v[100:101] op_sel_hi:[1,0,1]
	v_pk_fma_f32 v[98:99], v[22:23], v[28:29], v[98:99] op_sel_hi:[1,0,1]
	v_pk_fma_f32 v[106:107], v[24:25], v[36:37], v[106:107] op_sel_hi:[1,0,1]
	v_pk_fma_f32 v[108:109], v[22:23], v[36:37], v[108:109] op_sel_hi:[1,0,1]
	v_pk_fma_f32 v[120:121], v[24:25], v[72:73], v[120:121] op_sel_hi:[1,0,1]
	v_pk_fma_f32 v[118:119], v[22:23], v[72:73], v[118:119] op_sel_hi:[1,0,1]
	v_pk_fma_f32 v[84:85], v[24:25], v[2:3], v[84:85] op_sel_hi:[1,0,1]
	v_pk_fma_f32 v[76:77], v[22:23], v[2:3], v[76:77] op_sel_hi:[1,0,1]
	v_pk_fma_f32 v[126:127], v[24:25], v[80:81], v[126:127] op_sel_hi:[1,0,1]
	v_pk_fma_f32 v[124:125], v[22:23], v[80:81], v[124:125] op_sel_hi:[1,0,1]
	v_pk_fma_f32 v[78:79], v[24:25], v[80:81], v[78:79] op_sel:[0,1,0]
	v_pk_fma_f32 v[80:81], v[22:23], v[80:81], v[128:129] op_sel:[0,1,0]
	ds_read_b128 v[22:25], v208 offset:640
	ds_read_b128 v[26:29], v208 offset:656
	ds_read_b128 v[30:33], v208 offset:672
	ds_read_b128 v[34:37], v208 offset:688
	ds_read2_b64 v[70:73], v208 offset0:88 offset1:108
	s_waitcnt lgkmcnt(4)
	v_mov_b32_e32 v2, v25
	v_pk_fma_f32 v[128:129], v[18:19], v[22:23], v[132:133] op_sel_hi:[1,0,1]
	v_pk_fma_f32 v[130:131], v[20:21], v[22:23], v[130:131] op_sel_hi:[1,0,1]
	s_waitcnt lgkmcnt(1)
	v_pk_fma_f32 v[90:91], v[18:19], v[34:35], v[90:91] op_sel_hi:[1,0,1]
	v_pk_fma_f32 v[92:93], v[20:21], v[34:35], v[92:93] op_sel_hi:[1,0,1]
	v_pk_fma_f32 v[94:95], v[18:19], v[22:23], v[94:95] op_sel:[0,1,0]
	v_pk_fma_f32 v[96:97], v[20:21], v[22:23], v[96:97] op_sel:[0,1,0]
	v_pk_fma_f32 v[82:83], v[18:19], v[34:35], v[82:83] op_sel:[0,1,0]
	v_pk_fma_f32 v[34:35], v[20:21], v[34:35], v[74:75] op_sel:[0,1,0]
	v_pk_fma_f32 v[74:75], v[18:19], v[24:25], v[102:103] op_sel_hi:[1,0,1]
	v_pk_fma_f32 v[102:103], v[20:21], v[24:25], v[104:105] op_sel_hi:[1,0,1]
	v_pk_fma_f32 v[4:5], v[18:19], v[2:3], v[4:5] op_sel_hi:[1,0,1]
	v_pk_fma_f32 v[114:115], v[20:21], v[2:3], v[114:115] op_sel_hi:[1,0,1]
	v_mov_b32_e32 v2, v29
	ds_read_b128 v[22:25], v208 offset:800
	v_pk_fma_f32 v[110:111], v[18:19], v[2:3], v[110:111] op_sel_hi:[1,0,1]
	v_pk_fma_f32 v[112:113], v[20:21], v[2:3], v[112:113] op_sel_hi:[1,0,1]
	v_mov_b32_e32 v2, v33
	v_pk_fma_f32 v[104:105], v[18:19], v[32:33], v[108:109] op_sel_hi:[1,0,1]
	v_pk_fma_f32 v[108:109], v[18:19], v[36:37], v[118:119] op_sel_hi:[1,0,1]
	v_pk_fma_f32 v[118:119], v[20:21], v[36:37], v[120:121] op_sel_hi:[1,0,1]
	v_pk_fma_f32 v[116:117], v[18:19], v[2:3], v[116:117] op_sel_hi:[1,0,1]
	v_pk_fma_f32 v[120:121], v[20:21], v[2:3], v[122:123] op_sel_hi:[1,0,1]
	v_mov_b32_e32 v2, v37
	v_pk_fma_f32 v[132:133], v[18:19], v[26:27], v[136:137] op_sel_hi:[1,0,1]
	v_pk_fma_f32 v[134:135], v[20:21], v[26:27], v[134:135] op_sel_hi:[1,0,1]
	v_pk_fma_f32 v[136:137], v[18:19], v[30:31], v[140:141] op_sel_hi:[1,0,1]
	v_pk_fma_f32 v[138:139], v[20:21], v[30:31], v[138:139] op_sel_hi:[1,0,1]
	v_pk_fma_f32 v[86:87], v[18:19], v[26:27], v[86:87] op_sel:[0,1,0]
	v_pk_fma_f32 v[88:89], v[20:21], v[26:27], v[88:89] op_sel:[0,1,0]
	v_pk_fma_f32 v[140:141], v[18:19], v[30:31], v[180:181] op_sel:[0,1,0]
	v_pk_fma_f32 v[180:181], v[20:21], v[30:31], v[182:183] op_sel:[0,1,0]
	v_pk_fma_f32 v[98:99], v[18:19], v[28:29], v[98:99] op_sel_hi:[1,0,1]
	v_pk_fma_f32 v[100:101], v[20:21], v[28:29], v[100:101] op_sel_hi:[1,0,1]
	v_pk_fma_f32 v[106:107], v[20:21], v[32:33], v[106:107] op_sel_hi:[1,0,1]
	v_pk_fma_f32 v[36:37], v[18:19], v[2:3], v[76:77] op_sel_hi:[1,0,1]
	v_pk_fma_f32 v[76:77], v[20:21], v[2:3], v[84:85] op_sel_hi:[1,0,1]
	s_waitcnt lgkmcnt(1)
	v_pk_fma_f32 v[84:85], v[18:19], v[70:71], v[124:125] op_sel_hi:[1,0,1]
	v_pk_fma_f32 v[122:123], v[20:21], v[70:71], v[126:127] op_sel_hi:[1,0,1]
	v_pk_fma_f32 v[80:81], v[18:19], v[70:71], v[80:81] op_sel:[0,1,0]
	v_pk_fma_f32 v[70:71], v[20:21], v[70:71], v[78:79] op_sel:[0,1,0]
	ds_read_b128 v[18:21], v208 offset:816
	ds_read_b128 v[26:29], v208 offset:832
	ds_read_b128 v[30:33], v208 offset:848
	s_waitcnt lgkmcnt(3)
	v_mov_b32_e32 v2, v25
	v_pk_fma_f32 v[114:115], v[16:17], v[2:3], v[114:115] op_sel_hi:[1,0,1]
	v_pk_fma_f32 v[4:5], v[14:15], v[2:3], v[4:5] op_sel_hi:[1,0,1]
	s_waitcnt lgkmcnt(2)
	v_mov_b32_e32 v2, v21
	v_pk_fma_f32 v[112:113], v[16:17], v[2:3], v[112:113] op_sel_hi:[1,0,1]
	v_pk_fma_f32 v[110:111], v[14:15], v[2:3], v[110:111] op_sel_hi:[1,0,1]
	s_waitcnt lgkmcnt(1)
	v_mov_b32_e32 v2, v29
	v_pk_fma_f32 v[120:121], v[16:17], v[2:3], v[120:121] op_sel_hi:[1,0,1]
	v_pk_fma_f32 v[116:117], v[14:15], v[2:3], v[116:117] op_sel_hi:[1,0,1]
	s_waitcnt lgkmcnt(0)
	v_mov_b32_e32 v2, v33
	v_pk_fma_f32 v[78:79], v[16:17], v[22:23], v[130:131] op_sel_hi:[1,0,1]
	v_pk_fma_f32 v[124:125], v[14:15], v[22:23], v[128:129] op_sel_hi:[1,0,1]
	v_pk_fma_f32 v[126:127], v[16:17], v[18:19], v[134:135] op_sel_hi:[1,0,1]
	v_pk_fma_f32 v[128:129], v[14:15], v[18:19], v[132:133] op_sel_hi:[1,0,1]
	v_pk_fma_f32 v[130:131], v[16:17], v[26:27], v[138:139] op_sel_hi:[1,0,1]
	v_pk_fma_f32 v[132:133], v[14:15], v[26:27], v[136:137] op_sel_hi:[1,0,1]
	v_pk_fma_f32 v[92:93], v[16:17], v[30:31], v[92:93] op_sel_hi:[1,0,1]
	v_pk_fma_f32 v[90:91], v[14:15], v[30:31], v[90:91] op_sel_hi:[1,0,1]
	v_pk_fma_f32 v[96:97], v[16:17], v[22:23], v[96:97] op_sel:[0,1,0]
	v_pk_fma_f32 v[94:95], v[14:15], v[22:23], v[94:95] op_sel:[0,1,0]
	v_pk_fma_f32 v[88:89], v[16:17], v[18:19], v[88:89] op_sel:[0,1,0]
	v_pk_fma_f32 v[86:87], v[14:15], v[18:19], v[86:87] op_sel:[0,1,0]
	v_pk_fma_f32 v[134:135], v[16:17], v[26:27], v[180:181] op_sel:[0,1,0]
	v_pk_fma_f32 v[136:137], v[14:15], v[26:27], v[140:141] op_sel:[0,1,0]
	v_pk_fma_f32 v[34:35], v[16:17], v[30:31], v[34:35] op_sel:[0,1,0]
	v_pk_fma_f32 v[82:83], v[14:15], v[30:31], v[82:83] op_sel:[0,1,0]
	v_pk_fma_f32 v[102:103], v[16:17], v[24:25], v[102:103] op_sel_hi:[1,0,1]
	v_pk_fma_f32 v[74:75], v[14:15], v[24:25], v[74:75] op_sel_hi:[1,0,1]
	v_pk_fma_f32 v[100:101], v[16:17], v[20:21], v[100:101] op_sel_hi:[1,0,1]
	v_pk_fma_f32 v[98:99], v[14:15], v[20:21], v[98:99] op_sel_hi:[1,0,1]
	v_pk_fma_f32 v[106:107], v[16:17], v[28:29], v[106:107] op_sel_hi:[1,0,1]
	v_pk_fma_f32 v[104:105], v[14:15], v[28:29], v[104:105] op_sel_hi:[1,0,1]
	v_pk_fma_f32 v[118:119], v[16:17], v[32:33], v[118:119] op_sel_hi:[1,0,1]
	v_pk_fma_f32 v[108:109], v[14:15], v[32:33], v[108:109] op_sel_hi:[1,0,1]
	v_pk_fma_f32 v[76:77], v[16:17], v[2:3], v[76:77] op_sel_hi:[1,0,1]
	v_pk_fma_f32 v[36:37], v[14:15], v[2:3], v[36:37] op_sel_hi:[1,0,1]
	v_pk_fma_f32 v[122:123], v[16:17], v[72:73], v[122:123] op_sel_hi:[1,0,1]
	v_pk_fma_f32 v[84:85], v[14:15], v[72:73], v[84:85] op_sel_hi:[1,0,1]
	v_pk_fma_f32 v[70:71], v[16:17], v[72:73], v[70:71] op_sel:[0,1,0]
	v_pk_fma_f32 v[72:73], v[14:15], v[72:73], v[80:81] op_sel:[0,1,0]
	ds_read_b128 v[14:17], v208 offset:960
	ds_read_b128 v[18:21], v208 offset:976
	ds_read_b128 v[22:25], v208 offset:992
	ds_read_b128 v[26:29], v208 offset:1008
	ds_read2_b64 v[30:33], v208 offset0:128 offset1:148
	s_waitcnt lgkmcnt(4)
	v_mov_b32_e32 v2, v17
	v_pk_fma_f32 v[80:81], v[10:11], v[14:15], v[124:125] op_sel_hi:[1,0,1]
	v_pk_fma_f32 v[78:79], v[12:13], v[14:15], v[78:79] op_sel_hi:[1,0,1]
	s_waitcnt lgkmcnt(3)
	v_pk_fma_f32 v[124:125], v[10:11], v[18:19], v[128:129] op_sel_hi:[1,0,1]
	s_waitcnt lgkmcnt(2)
	v_pk_fma_f32 v[128:129], v[10:11], v[22:23], v[132:133] op_sel_hi:[1,0,1]
	s_waitcnt lgkmcnt(1)
	v_pk_fma_f32 v[90:91], v[10:11], v[26:27], v[90:91] op_sel_hi:[1,0,1]
	v_pk_fma_f32 v[92:93], v[12:13], v[26:27], v[92:93] op_sel_hi:[1,0,1]
	v_pk_fma_f32 v[94:95], v[10:11], v[14:15], v[94:95] op_sel:[0,1,0]
	v_pk_fma_f32 v[96:97], v[12:13], v[14:15], v[96:97] op_sel:[0,1,0]
	v_pk_fma_f32 v[132:133], v[10:11], v[22:23], v[136:137] op_sel:[0,1,0]
	v_pk_fma_f32 v[136:137], v[10:11], v[26:27], v[82:83] op_sel:[0,1,0]
	v_pk_fma_f32 v[26:27], v[12:13], v[26:27], v[34:35] op_sel:[0,1,0]
	v_pk_fma_f32 v[34:35], v[10:11], v[16:17], v[74:75] op_sel_hi:[1,0,1]
	v_pk_fma_f32 v[102:103], v[12:13], v[16:17], v[102:103] op_sel_hi:[1,0,1]
	v_pk_fma_f32 v[4:5], v[10:11], v[2:3], v[4:5] op_sel_hi:[1,0,1]
	v_pk_fma_f32 v[114:115], v[12:13], v[2:3], v[114:115] op_sel_hi:[1,0,1]
	v_mov_b32_e32 v2, v21
	ds_read_b128 v[14:17], v208 offset:1120
	v_pk_fma_f32 v[110:111], v[10:11], v[2:3], v[110:111] op_sel_hi:[1,0,1]
	v_pk_fma_f32 v[112:113], v[12:13], v[2:3], v[112:113] op_sel_hi:[1,0,1]
	v_mov_b32_e32 v2, v25
	v_pk_fma_f32 v[184:185], v[10:11], v[2:3], v[116:117] op_sel_hi:[1,0,1]
	v_pk_fma_f32 v[186:187], v[12:13], v[2:3], v[120:121] op_sel_hi:[1,0,1]
	v_mov_b32_e32 v2, v29
	v_pk_fma_f32 v[126:127], v[12:13], v[18:19], v[126:127] op_sel_hi:[1,0,1]
	v_pk_fma_f32 v[130:131], v[12:13], v[22:23], v[130:131] op_sel_hi:[1,0,1]
	v_pk_fma_f32 v[86:87], v[10:11], v[18:19], v[86:87] op_sel:[0,1,0]
	v_pk_fma_f32 v[88:89], v[12:13], v[18:19], v[88:89] op_sel:[0,1,0]
	v_pk_fma_f32 v[134:135], v[12:13], v[22:23], v[134:135] op_sel:[0,1,0]
	v_pk_fma_f32 v[98:99], v[10:11], v[20:21], v[98:99] op_sel_hi:[1,0,1]
	v_pk_fma_f32 v[100:101], v[12:13], v[20:21], v[100:101] op_sel_hi:[1,0,1]
	v_pk_fma_f32 v[138:139], v[10:11], v[24:25], v[104:105] op_sel_hi:[1,0,1]
	v_pk_fma_f32 v[140:141], v[12:13], v[24:25], v[106:107] op_sel_hi:[1,0,1]
	v_pk_fma_f32 v[180:181], v[10:11], v[28:29], v[108:109] op_sel_hi:[1,0,1]
	v_pk_fma_f32 v[182:183], v[12:13], v[28:29], v[118:119] op_sel_hi:[1,0,1]
	v_pk_fma_f32 v[28:29], v[10:11], v[2:3], v[36:37] op_sel_hi:[1,0,1]
	v_pk_fma_f32 v[36:37], v[12:13], v[2:3], v[76:77] op_sel_hi:[1,0,1]
	s_waitcnt lgkmcnt(1)
	v_pk_fma_f32 v[188:189], v[10:11], v[30:31], v[84:85] op_sel_hi:[1,0,1]
	v_pk_fma_f32 v[190:191], v[12:13], v[30:31], v[122:123] op_sel_hi:[1,0,1]
	v_pk_fma_f32 v[192:193], v[10:11], v[30:31], v[72:73] op_sel:[0,1,0]
	v_pk_fma_f32 v[30:31], v[12:13], v[30:31], v[70:71] op_sel:[0,1,0]
	ds_read_b128 v[10:13], v208 offset:1136
	ds_read_b128 v[18:21], v208 offset:1152
	ds_read_b128 v[22:25], v208 offset:1168
	s_waitcnt lgkmcnt(3)
	v_mov_b32_e32 v2, v17
	v_pk_fma_f32 v[116:117], v[8:9], v[2:3], v[114:115] op_sel_hi:[1,0,1]
	v_pk_fma_f32 v[114:115], v[6:7], v[2:3], v[4:5] op_sel_hi:[1,0,1]
	s_waitcnt lgkmcnt(2)
	v_mov_b32_e32 v2, v13
	v_pk_fma_f32 v[112:113], v[8:9], v[2:3], v[112:113] op_sel_hi:[1,0,1]
	v_pk_fma_f32 v[110:111], v[6:7], v[2:3], v[110:111] op_sel_hi:[1,0,1]
	s_waitcnt lgkmcnt(1)
	v_mov_b32_e32 v2, v21
	v_pk_fma_f32 v[76:77], v[8:9], v[10:11], v[126:127] op_sel_hi:[1,0,1]
	v_pk_fma_f32 v[70:71], v[6:7], v[18:19], v[128:129] op_sel_hi:[1,0,1]
	v_pk_fma_f32 v[128:129], v[8:9], v[2:3], v[186:187] op_sel_hi:[1,0,1]
	v_pk_fma_f32 v[126:127], v[6:7], v[2:3], v[184:185] op_sel_hi:[1,0,1]
	s_waitcnt lgkmcnt(0)
	v_mov_b32_e32 v2, v25
	v_pk_fma_f32 v[84:85], v[8:9], v[14:15], v[78:79] op_sel_hi:[1,0,1]
	v_pk_fma_f32 v[82:83], v[6:7], v[14:15], v[80:81] op_sel_hi:[1,0,1]
	v_pk_fma_f32 v[74:75], v[6:7], v[10:11], v[124:125] op_sel_hi:[1,0,1]
	v_pk_fma_f32 v[72:73], v[8:9], v[18:19], v[130:131] op_sel_hi:[1,0,1]
	v_pk_fma_f32 v[92:93], v[8:9], v[22:23], v[92:93] op_sel_hi:[1,0,1]
	v_pk_fma_f32 v[90:91], v[6:7], v[22:23], v[90:91] op_sel_hi:[1,0,1]
	v_pk_fma_f32 v[96:97], v[8:9], v[14:15], v[96:97] op_sel:[0,1,0]
	v_pk_fma_f32 v[94:95], v[6:7], v[14:15], v[94:95] op_sel:[0,1,0]
	v_pk_fma_f32 v[88:89], v[8:9], v[10:11], v[88:89] op_sel:[0,1,0]
	v_pk_fma_f32 v[86:87], v[6:7], v[10:11], v[86:87] op_sel:[0,1,0]
	v_pk_fma_f32 v[80:81], v[8:9], v[18:19], v[134:135] op_sel:[0,1,0]
	v_pk_fma_f32 v[78:79], v[6:7], v[18:19], v[132:133] op_sel:[0,1,0]
	v_pk_fma_f32 v[108:109], v[8:9], v[22:23], v[26:27] op_sel:[0,1,0]
	v_pk_fma_f32 v[106:107], v[6:7], v[22:23], v[136:137] op_sel:[0,1,0]
	v_pk_fma_f32 v[104:105], v[8:9], v[16:17], v[102:103] op_sel_hi:[1,0,1]
	v_pk_fma_f32 v[102:103], v[6:7], v[16:17], v[34:35] op_sel_hi:[1,0,1]
	v_pk_fma_f32 v[100:101], v[8:9], v[12:13], v[100:101] op_sel_hi:[1,0,1]
	v_pk_fma_f32 v[98:99], v[6:7], v[12:13], v[98:99] op_sel_hi:[1,0,1]
	v_pk_fma_f32 v[120:121], v[8:9], v[20:21], v[140:141] op_sel_hi:[1,0,1]
	v_pk_fma_f32 v[118:119], v[6:7], v[20:21], v[138:139] op_sel_hi:[1,0,1]
	v_pk_fma_f32 v[124:125], v[8:9], v[24:25], v[182:183] op_sel_hi:[1,0,1]
	v_pk_fma_f32 v[122:123], v[6:7], v[24:25], v[180:181] op_sel_hi:[1,0,1]
	v_pk_fma_f32 v[132:133], v[8:9], v[2:3], v[36:37] op_sel_hi:[1,0,1]
	v_pk_fma_f32 v[130:131], v[6:7], v[2:3], v[28:29] op_sel_hi:[1,0,1]
	v_pk_fma_f32 v[136:137], v[8:9], v[32:33], v[190:191] op_sel_hi:[1,0,1]
	v_pk_fma_f32 v[134:135], v[6:7], v[32:33], v[188:189] op_sel_hi:[1,0,1]
	v_pk_fma_f32 v[140:141], v[8:9], v[32:33], v[30:31] op_sel:[0,1,0]
	v_pk_fma_f32 v[138:139], v[6:7], v[32:33], v[192:193] op_sel:[0,1,0]
	s_waitcnt vmcnt(0)
	v_mov_b64_e32 v[6:7], v[66:67]
	v_mov_b64_e32 v[10:11], v[62:63]
	v_mov_b64_e32 v[14:15], v[58:59]
	v_mov_b64_e32 v[18:19], v[54:55]
	v_mov_b64_e32 v[22:23], v[50:51]
	v_mov_b64_e32 v[26:27], v[46:47]
	v_mov_b64_e32 v[30:31], v[42:43]
	v_mov_b64_e32 v[34:35], v[38:39]
	v_mov_b64_e32 v[8:9], v[68:69]
	v_mov_b64_e32 v[12:13], v[64:65]
	v_mov_b64_e32 v[16:17], v[60:61]
	v_mov_b64_e32 v[20:21], v[56:57]
	v_mov_b64_e32 v[24:25], v[52:53]
	v_mov_b64_e32 v[28:29], v[48:49]
	v_mov_b64_e32 v[32:33], v[44:45]
	v_mov_b64_e32 v[36:37], v[40:41]
